# nt (non-temporal) hint on the read-once f32 x row loads in prep and mid phases
# speedup vs baseline: 1.0064x; 1.0064x over previous
; DI void prep_phase(const Params& p, LAS unsigned char* lds) {
;     ...
;     f32x4 wv[4];
; #pragma unroll
;     for (int j = 0; j < 4; ++j) wv[j] = ((const f32x4*)p.pre)[lane + 64 * j];
;     f32x4 nv[4];
;     if (gw < M) { const f32x4* xr = (const f32x4*)h0_row(p, gw);
; #pragma unroll
;         for (int j = 0; j < 4; ++j) nv[j] = xr[lane + 64 * j]; }
;     for (int r = gw; r < M; r += NGW) {
;         f32x4 v[4]; float s = 0.f;
; #pragma unroll
;         for (int j = 0; j < 4; ++j) v[j] = nv[j];
;         if (r + NGW < M) { const f32x4* xn = (const f32x4*)h0_row(p, r + NGW);
; #pragma unroll
;             for (int j = 0; j < 4; ++j) nv[j] = xn[lane + 64 * j]; }
.LBB0_34:
	s_or_b64 exec, exec, s[0:1]
	s_mov_b32 s0, 0x10100
	v_cmp_gt_i32_e32 vcc, s0, v50
	s_and_saveexec_b64 s[4:5], vcc
	s_cbranch_execz .LBB0_45
	v_lshlrev_b32_e32 v52, 4, v34
	s_waitcnt lgkmcnt(0)
	global_load_dwordx4 v[2:5], v52, s[40:41]
	global_load_dwordx4 v[6:9], v52, s[40:41] offset:1024
	global_load_dwordx4 v[10:13], v52, s[40:41] offset:2048
	global_load_dwordx4 v[14:17], v52, s[40:41] offset:3072
	s_mov_b32 s0, 0xffff
	v_mov_b32_e32 v21, 0
	v_cmp_lt_i32_e32 vcc, s0, v50
	v_ashrrev_i32_e32 v51, 31, v50
	s_and_saveexec_b64 s[0:1], vcc
	s_xor_b64 s[0:1], exec, s[0:1]
	v_lshlrev_b32_e32 v1, 12, v50
	v_and_b32_e32 v20, 0xf000, v1
	v_lshl_add_u64 v[18:19], s[38:39], 0, v[20:21]
	s_andn2_saveexec_b64 s[0:1], s[0:1]
	v_lshlrev_b64 v[18:19], 12, v[50:51]
	v_lshl_add_u64 v[18:19], s[36:37], 0, v[18:19]
	s_or_b64 exec, exec, s[0:1]
	v_mov_b32_e32 v53, 0
	v_lshl_add_u64 v[36:37], v[18:19], 0, v[52:53]
	global_load_dwordx4 v[30:33], v[36:37], off nt
	global_load_dwordx4 v[26:29], v[36:37], off offset:1024 nt
	global_load_dwordx4 v[22:25], v[36:37], off offset:2048 nt
	global_load_dwordx4 v[18:21], v[36:37], off offset:3072 nt
	v_mbcnt_lo_u32_b32 v35, -1, 0
	v_lshlrev_b64 v[36:37], 11, v[50:51]
	v_add_u32_e32 v38, s34, v50
	v_mbcnt_hi_u32_b32 v40, -1, v35
	v_lshl_or_b32 v36, v34, 3, v36
	v_ashrrev_i32_e32 v39, 31, v38
	v_and_b32_e32 v41, 64, v40
	v_lshlrev_b32_e32 v51, 10, v38
	v_xor_b32_e32 v42, 1, v40
	v_lshl_add_u64 v[34:35], s[30:31], 0, v[36:37]
	v_lshlrev_b64 v[36:37], 12, v[38:39]
	v_add_u32_e32 v38, 64, v41
	s_mov_b64 s[0:1], 0x1401000
	v_xor_b32_e32 v43, 2, v40
	v_cmp_lt_i32_e32 vcc, v42, v38
	v_xor_b32_e32 v44, 4, v40
	v_lshl_add_u64 v[54:55], v[34:35], 0, s[0:1]
	v_cndmask_b32_e32 v34, v40, v42, vcc
	v_cmp_lt_i32_e32 vcc, v43, v38
	v_xor_b32_e32 v45, 8, v40
	v_xor_b32_e32 v46, 16, v40
	v_cndmask_b32_e32 v35, v40, v43, vcc
	v_cmp_lt_i32_e32 vcc, v44, v38
	v_lshl_add_u64 v[56:57], s[36:37], 0, v[36:37]
	v_xor_b32_e32 v47, 32, v40
	v_cndmask_b32_e32 v36, v40, v44, vcc
	v_cmp_lt_i32_e32 vcc, v45, v38
	s_ashr_i32 s35, s34, 31
	v_lshlrev_b32_e32 v58, 2, v34
	v_cndmask_b32_e32 v37, v40, v45, vcc
	v_cmp_lt_i32_e32 vcc, v46, v38
	v_lshlrev_b32_e32 v59, 2, v35
	v_lshlrev_b32_e32 v60, 2, v36
	v_cndmask_b32_e32 v39, v40, v46, vcc
	v_cmp_lt_i32_e32 vcc, v47, v38
	v_lshlrev_b32_e32 v61, 2, v37
	v_lshlrev_b32_e32 v62, 2, v39
	v_cndmask_b32_e32 v38, v40, v47, vcc
	v_lshlrev_b32_e32 v63, 2, v38
	s_lshl_b32 s3, s54, 13
	s_mov_b64 s[8:9], 0
	s_mov_b32 s11, 0x10100
	s_mov_b32 s20, 0x100ff
	s_mov_b32 s21, 0xffff
	v_mov_b32_e32 v1, 0x358637bd
	s_mov_b32 s24, 0x800000
	s_lshl_b64 s[12:13], s[34:35], 11
	s_lshl_b64 s[14:15], s[34:35], 12
	s_waitcnt vmcnt(3)
	v_mov_b64_e32 v[36:37], v[32:33]
	s_waitcnt vmcnt(2)
	v_mov_b64_e32 v[40:41], v[28:29]
	s_waitcnt vmcnt(1)
	v_mov_b64_e32 v[44:45], v[24:25]
	s_waitcnt vmcnt(0)
	v_mov_b64_e32 v[48:49], v[20:21]
	v_mov_b64_e32 v[34:35], v[30:31]
	v_mov_b64_e32 v[38:39], v[26:27]
	v_mov_b64_e32 v[42:43], v[22:23]
	v_mov_b64_e32 v[46:47], v[18:19]
	s_branch .LBB0_42
.LBB0_40:
	s_or_b64 exec, exec, s[18:19]
	v_lshl_add_u64 v[64:65], v[34:35], 0, v[52:53]
	global_load_dwordx4 v[34:37], v[64:65], off nt
	global_load_dwordx4 v[38:41], v[64:65], off offset:1024 nt
	global_load_dwordx4 v[42:45], v[64:65], off offset:2048 nt
	global_load_dwordx4 v[46:49], v[64:65], off offset:3072 nt

; DI void mid_phase(const Params& p) {
;     ...
;     f32x4 wpost[4], wpre[4];
; #pragma unroll
;     for (int j = 0; j < 4; ++j) { wpost[j] = ((const f32x4*)p.post)[lane + 64 * j]; wpre[j] = ((const f32x4*)(p.pre + D))[lane + 64 * j]; }
;     u32x2 nyw[4]; f32x4 nhv[4];
;     if (gw < M) { const u32x2* yr = (const u32x2*)((const bf16_t*)(ws + OFF_GF) + (size_t)gw * D); const f32x4* hr = (const f32x4*)h0_row(p, gw);
; #pragma unroll
;         for (int j = 0; j < 4; ++j) { nyw[j] = yr[lane + 64 * j]; nhv[j] = hr[lane + 64 * j]; } }
.LBB0_615:
	s_or_b64 exec, exec, s[0:1]
	s_waitcnt lgkmcnt(0)
	v_mov_b32_e32 v0, v146
	s_barrier
	s_mov_b32 s0, 0x10100
	v_ashrrev_i32_e32 v1, 6, v0
	v_add_u32_e32 v64, s33, v1
	v_cmp_gt_i32_e32 vcc, s0, v64
	s_and_saveexec_b64 s[4:5], vcc
	s_cbranch_execz .LBB0_632
	v_and_b32_e32 v36, 63, v0
	s_add_u32 s0, s40, 0x1000
	v_lshlrev_b32_e32 v66, 4, v36
	s_addc_u32 s1, s41, 0
	v_or_b32_e32 v28, 0x400, v66
	global_load_dwordx4 v[0:3], v66, s[0:1]
	global_load_dwordx4 v[4:7], v66, s[42:43]
	global_load_dwordx4 v[8:11], v66, s[42:43] offset:1024
	v_or_b32_e32 v29, 0x800, v66
	global_load_dwordx4 v[12:15], v28, s[0:1]
	global_load_dwordx4 v[16:19], v29, s[0:1]
	global_load_dwordx4 v[20:23], v66, s[42:43] offset:2048
	global_load_dwordx4 v[24:27], v66, s[42:43] offset:3072
	v_or_b32_e32 v28, 0xc00, v66
	global_load_dwordx4 v[28:31], v28, s[0:1]
	s_mov_b32 s0, 0xffff
	v_mov_b32_e32 v35, 0
	v_ashrrev_i32_e32 v65, 31, v64
	v_cmp_lt_i32_e32 vcc, s0, v64
	s_and_saveexec_b64 s[0:1], vcc
	s_xor_b64 s[0:1], exec, s[0:1]
	v_lshlrev_b32_e32 v32, 12, v64
	v_and_b32_e32 v34, 0xf000, v32
	v_lshl_add_u64 v[32:33], s[38:39], 0, v[34:35]
	s_andn2_saveexec_b64 s[0:1], s[0:1]
	v_lshlrev_b64 v[32:33], 12, v[64:65]
	v_lshl_add_u64 v[32:33], s[36:37], 0, v[32:33]
	s_or_b64 exec, exec, s[0:1]
	v_lshlrev_b64 v[44:45], 11, v[64:65]
	v_mov_b32_e32 v67, 0
	v_lshlrev_b32_e32 v68, 3, v36
	v_lshl_add_u64 v[34:35], s[26:27], 0, v[44:45]
	v_lshl_add_u64 v[46:47], v[32:33], 0, v[66:67]
	v_mov_b32_e32 v70, v68
	v_mov_b32_e32 v71, v67
	v_lshl_add_u64 v[48:49], v[34:35], 0, v[70:71]
	global_load_dwordx4 v[32:35], v[46:47], off offset:3072 nt
	global_load_dwordx4 v[36:39], v[46:47], off offset:2048 nt
	global_load_dwordx4 v[40:43], v[46:47], off offset:1024 nt
	global_load_dwordx4 v[52:55], v[46:47], off nt
	global_load_dwordx2 v[88:89], v[48:49], off offset:1536
	global_load_dwordx2 v[90:91], v[48:49], off offset:1024
	global_load_dwordx2 v[92:93], v[48:49], off offset:512
	global_load_dwordx2 v[94:95], v[48:49], off
	v_mbcnt_hi_u32_b32 v46, -1, v147
	v_and_b32_e32 v47, 64, v46
	v_add_u32_e32 v47, 64, v47
	v_xor_b32_e32 v48, 1, v46
	v_cmp_lt_i32_e32 vcc, v48, v47
	v_lshl_add_u64 v[72:73], s[30:31], 0, v[44:45]
	v_add_u32_e32 v44, s34, v64
	v_cndmask_b32_e32 v48, v46, v48, vcc
	v_lshlrev_b32_e32 v65, 2, v48
	v_xor_b32_e32 v48, 2, v46
	v_cmp_lt_i32_e32 vcc, v48, v47
	s_add_u32 s6, s30, 0x32501000
	v_ashrrev_i32_e32 v45, 31, v44
	v_cndmask_b32_e32 v48, v46, v48, vcc
	v_lshlrev_b32_e32 v96, 2, v48
	v_xor_b32_e32 v48, 4, v46
	v_cmp_lt_i32_e32 vcc, v48, v47
	s_addc_u32 s7, s31, 0
	s_ashr_i32 s35, s34, 31
	v_cndmask_b32_e32 v48, v46, v48, vcc
	v_lshlrev_b32_e32 v97, 2, v48
	v_xor_b32_e32 v48, 8, v46
	v_cmp_lt_i32_e32 vcc, v48, v47
	v_lshlrev_b32_e32 v101, 10, v44
	s_lshl_b64 s[8:9], s[34:35], 11
	v_cndmask_b32_e32 v48, v46, v48, vcc
	v_lshlrev_b32_e32 v98, 2, v48
	v_xor_b32_e32 v48, 16, v46
	v_cmp_lt_i32_e32 vcc, v48, v47
	s_lshl_b32 s20, s54, 13
	s_lshl_b64 s[12:13], s[34:35], 12
	v_cndmask_b32_e32 v48, v46, v48, vcc
	v_lshlrev_b32_e32 v99, 2, v48
	v_xor_b32_e32 v48, 32, v46
	v_cmp_lt_i32_e32 vcc, v48, v47
	s_mov_b64 s[14:15], 0
	s_mov_b32 s21, 0xffff
	v_cndmask_b32_e32 v46, v46, v48, vcc
	v_lshlrev_b32_e32 v100, 2, v46
	v_lshlrev_b64 v[46:47], 12, v[44:45]
	v_lshlrev_b64 v[44:45], 11, v[44:45]
	v_lshl_add_u64 v[74:75], s[36:37], 0, v[46:47]
	v_lshl_add_u64 v[76:77], s[30:31], 0, v[44:45]
	s_mov_b32 s35, 0x10100
	s_mov_b32 s36, 0x100ff
	v_mov_b32_e32 v102, 0x358637bd
	s_mov_b32 s37, 0x800000
	s_mov_b32 s40, 0x1401000
	s_branch .LBB0_622

; DI void bl_of(int r, int& b, int& l) { if (r < MMAIN) { b = r >> 12; l = (r & (SEQ - 1)) + NMETA; } else { b = (r - MMAIN) >> 4; l = (r - MMAIN) & (NMETA - 1); } }
; DI float bf_lo(unsigned u) { return __uint_as_float(u << 16); }
; DI float bf_hi(unsigned u) { return __uint_as_float(u & 0xffff0000u); }
; DI void mid_phase(const Params& p) {
;     ...
;     for (int r = gw; r < M; r += NGW) {
;         int b, l; bl_of(r, b, l);
;         f32x4 y[4], hv[4]; float s = 0.f;
; #pragma unroll
;         for (int j = 0; j < 4; ++j) { const u32x2 yw = nyw[j]; y[j] = (f32x4){bf_lo(yw.x), bf_hi(yw.x), bf_lo(yw.y), bf_hi(yw.y)}; hv[j] = nhv[j]; }
;         if (r + NGW < M) { const u32x2* yr = (const u32x2*)((const bf16_t*)(ws + OFF_GF) + (size_t)(r + NGW) * D); const f32x4* hr = (const f32x4*)h0_row(p, r + NGW);
; #pragma unroll
;             for (int j = 0; j < 4; ++j) { nyw[j] = yr[lane + 64 * j]; nhv[j] = hr[lane + 64 * j]; } }
.LBB0_622:
	v_cmp_lt_i32_e32 vcc, s21, v64
	s_and_saveexec_b64 s[0:1], vcc
	s_xor_b64 s[0:1], exec, s[0:1]
	v_add_u32_e32 v44, 0xffff0000, v64
	v_lshrrev_b32_e32 v78, 4, v44
	v_and_b32_e32 v69, 15, v64
	s_andn2_saveexec_b64 s[0:1], s[0:1]
	v_and_b32_e32 v44, 0xfff, v64
	v_ashrrev_i32_e32 v78, 12, v64
	v_add_u32_e32 v69, 16, v44
	s_or_b64 exec, exec, s[0:1]
	v_add_u32_e32 v64, s34, v64
	s_waitcnt vmcnt(4)
	v_mov_b64_e32 v[44:45], v[52:53]
	v_mov_b64_e32 v[50:51], v[42:43]
	v_mov_b64_e32 v[58:59], v[38:39]
	v_mov_b64_e32 v[62:63], v[34:35]
	v_cmp_gt_i32_e32 vcc, s35, v64
	v_cmp_lt_i32_e64 s[0:1], s36, v64
	v_mov_b64_e32 v[46:47], v[54:55]
	v_mov_b64_e32 v[48:49], v[40:41]
	v_mov_b64_e32 v[56:57], v[36:37]
	v_mov_b64_e32 v[60:61], v[32:33]
	s_waitcnt vmcnt(0)
	v_mov_b64_e32 v[80:81], v[94:95]
	v_mov_b64_e32 v[82:83], v[92:93]
	v_mov_b64_e32 v[84:85], v[90:91]
	v_mov_b64_e32 v[86:87], v[88:89]
	s_and_saveexec_b64 s[16:17], vcc
	s_cbranch_execz .LBB0_630
	v_cmp_lt_i32_e32 vcc, s21, v64
	v_mov_b64_e32 v[44:45], v[74:75]
	s_and_saveexec_b64 s[18:19], vcc
	v_and_b32_e32 v44, 0x3c00, v101
	v_lshlrev_b32_e32 v44, 2, v44
	v_mov_b32_e32 v45, v67
	v_lshl_add_u64 v[44:45], s[38:39], 0, v[44:45]
	s_or_b64 exec, exec, s[18:19]
	v_lshl_add_u64 v[46:47], v[76:77], 0, v[70:71]
	v_add_co_u32_e32 v56, vcc, 0x2a101000, v46
	v_lshl_add_u64 v[60:61], v[44:45], 0, v[66:67]
	s_nop 0
	v_addc_co_u32_e32 v57, vcc, 0, v47, vcc
	global_load_dwordx4 v[44:47], v[60:61], off nt
	global_load_dwordx4 v[48:51], v[60:61], off offset:1024 nt
	global_load_dwordx2 v[80:81], v[56:57], off
	global_load_dwordx2 v[82:83], v[56:57], off offset:512
	global_load_dwordx2 v[84:85], v[56:57], off offset:1024
	global_load_dwordx2 v[86:87], v[56:57], off offset:1536
	s_nop 0
	global_load_dwordx4 v[56:59], v[60:61], off offset:2048 nt
	s_nop 0
	global_load_dwordx4 v[60:63], v[60:61], off offset:3072 nt
